# prep: same norm-gain hoist applied to the a_w_in transpose loop
# baseline (speedup 1.0000x reference)
; #define LAS __attribute__((address_space(3)))
; __device__ __forceinline__ void transpose_store(const float (&tv)[32], int K, int N, bf16_t* WT, const float* kscale, int half, LAS float* scr, int item, int lane) {
;     const int nblk = N / 32, kb = item / nblk, nb = item % nblk, k0 = 64 * kb, n0 = 32 * nb;
; #pragma unroll
;     for (int i = 0; i < 32; ++i) { const int kk = 2 * i + (lane >> 5); float v = tv[i]; if (kscale) v *= kscale[k0 + kk]; scr[kk * 33 + (lane & 31)] = v; }
;     asm volatile("s_waitcnt lgkmcnt(0)" ::: "memory");
.LBB0_385:
	s_ashr_i32 s23, s22, 31
	s_lshr_b32 s23, s23, 25
	s_add_i32 s22, s22, s23
	s_ashr_i32 s39, s22, 7
	v_cndmask_b32_e64 v96, 0, 1, s[58:59]
	v_cmp_ne_u32_e64 s[44:45], 1, v96
	s_andn2_b64 vcc, exec, s[58:59]
	s_lshl_b32 s22, s39, 6
	s_cbranch_vccnz .LBB0_387
	v_or_b32_e32 v96, s22, v66
	v_ashrrev_i32_e32 v97, 31, v96
	v_lshl_add_u64 v[96:97], v[96:97], 2, s[40:41]
	flat_load_dword v160, v[96:97]
	flat_load_dword v161, v[96:97] offset:8
	flat_load_dword v162, v[96:97] offset:16
	flat_load_dword v163, v[96:97] offset:24
	flat_load_dword v164, v[96:97] offset:32
	flat_load_dword v165, v[96:97] offset:40
	flat_load_dword v166, v[96:97] offset:48
	flat_load_dword v167, v[96:97] offset:56
	flat_load_dword v168, v[96:97] offset:64
	flat_load_dword v169, v[96:97] offset:72
	flat_load_dword v170, v[96:97] offset:80
	flat_load_dword v171, v[96:97] offset:88
	flat_load_dword v172, v[96:97] offset:96
	flat_load_dword v173, v[96:97] offset:104
	flat_load_dword v174, v[96:97] offset:112
	flat_load_dword v175, v[96:97] offset:120
	flat_load_dword v176, v[96:97] offset:128
	flat_load_dword v177, v[96:97] offset:136
	flat_load_dword v178, v[96:97] offset:144
	flat_load_dword v179, v[96:97] offset:152
	flat_load_dword v180, v[96:97] offset:160
	flat_load_dword v181, v[96:97] offset:168
	flat_load_dword v182, v[96:97] offset:176
	flat_load_dword v183, v[96:97] offset:184
	flat_load_dword v184, v[96:97] offset:192
	flat_load_dword v185, v[96:97] offset:200
	flat_load_dword v186, v[96:97] offset:208
	flat_load_dword v187, v[96:97] offset:216
	flat_load_dword v188, v[96:97] offset:224
	flat_load_dword v189, v[96:97] offset:232
	flat_load_dword v190, v[96:97] offset:240
	flat_load_dword v191, v[96:97] offset:248
	s_waitcnt vmcnt(0) lgkmcnt(0)
	v_mul_f32_e32 v0, v0, v160
	v_mul_f32_e32 v1, v1, v161
	v_mul_f32_e32 v2, v2, v162
	v_mul_f32_e32 v3, v3, v163
	v_mul_f32_e32 v4, v4, v164
	v_mul_f32_e32 v5, v5, v165
	v_mul_f32_e32 v6, v6, v166
	v_mul_f32_e32 v7, v7, v167
	v_mul_f32_e32 v8, v8, v168
	v_mul_f32_e32 v9, v9, v169
	v_mul_f32_e32 v10, v10, v170
	v_mul_f32_e32 v11, v11, v171
	v_mul_f32_e32 v12, v12, v172
	v_mul_f32_e32 v13, v13, v173
	v_mul_f32_e32 v14, v14, v174
	v_mul_f32_e32 v15, v15, v175
	v_mul_f32_e32 v16, v16, v176
	v_mul_f32_e32 v17, v17, v177
	v_mul_f32_e32 v18, v18, v178
	v_mul_f32_e32 v19, v19, v179
	v_mul_f32_e32 v20, v20, v180
	v_mul_f32_e32 v21, v21, v181
	v_mul_f32_e32 v22, v22, v182
	v_mul_f32_e32 v23, v23, v183
	v_mul_f32_e32 v24, v24, v184
	v_mul_f32_e32 v25, v25, v185
	v_mul_f32_e32 v26, v26, v186
	v_mul_f32_e32 v27, v27, v187
	v_mul_f32_e32 v28, v28, v188
	v_mul_f32_e32 v29, v29, v189
	v_mul_f32_e32 v30, v30, v190
	v_mul_f32_e32 v31, v31, v191
.LBB0_387:
	s_and_b64 vcc, exec, s[44:45]
	s_waitcnt vmcnt(0) lgkmcnt(0)
	ds_write_b32 v104, v0
	s_cbranch_vccnz .LBB0_389
	s_ashr_i32 s23, s22, 31
.LBB0_389:
	v_add_u32_e32 v0, v103, v105
	s_and_b64 vcc, exec, s[44:45]
	ds_write_b32 v0, v1
	s_cbranch_vccnz .LBB0_391
	s_ashr_i32 s23, s22, 31
.LBB0_391:
	v_add_u32_e32 v0, v103, v106
	s_and_b64 vcc, exec, s[44:45]
	ds_write_b32 v0, v2
	s_cbranch_vccnz .LBB0_393
	s_ashr_i32 s23, s22, 31
.LBB0_393:
	v_add_u32_e32 v0, v103, v107
	s_and_b64 vcc, exec, s[44:45]
	ds_write_b32 v0, v3
	s_cbranch_vccnz .LBB0_395
	s_ashr_i32 s23, s22, 31
.LBB0_395:
	v_add_u32_e32 v0, v103, v108
	s_and_b64 vcc, exec, s[44:45]
	ds_write_b32 v0, v4
	s_cbranch_vccnz .LBB0_397
	s_ashr_i32 s23, s22, 31
.LBB0_397:
	v_add_u32_e32 v0, v103, v109
	s_and_b64 vcc, exec, s[44:45]
	ds_write_b32 v0, v5
	s_cbranch_vccnz .LBB0_399
	s_ashr_i32 s23, s22, 31
; #define LAS __attribute__((address_space(3)))
; __device__ __forceinline__ void transpose_store(const float (&tv)[32], int K, int N, bf16_t* WT, const float* kscale, int half, LAS float* scr, int item, int lane) {
;     const int nblk = N / 32, kb = item / nblk, nb = item % nblk, k0 = 64 * kb, n0 = 32 * nb;
; #pragma unroll
;     for (int i = 0; i < 32; ++i) { const int kk = 2 * i + (lane >> 5); float v = tv[i]; if (kscale) v *= kscale[k0 + kk]; scr[kk * 33 + (lane & 31)] = v; }
;     asm volatile("s_waitcnt lgkmcnt(0)" ::: "memory");
.LBB0_399:
	v_add_u32_e32 v0, v103, v110
	s_and_b64 vcc, exec, s[44:45]
	ds_write_b32 v0, v6
	s_cbranch_vccnz .LBB0_401
	s_ashr_i32 s23, s22, 31
.LBB0_401:
	v_add_u32_e32 v0, v103, v111
	s_and_b64 vcc, exec, s[44:45]
	ds_write_b32 v0, v7
	s_cbranch_vccnz .LBB0_403
	s_ashr_i32 s23, s22, 31
.LBB0_403:
	v_add_u32_e32 v0, v103, v112
	s_and_b64 vcc, exec, s[44:45]
	ds_write_b32 v0, v8
	s_cbranch_vccnz .LBB0_405
	s_ashr_i32 s23, s22, 31
.LBB0_405:
	v_add_u32_e32 v0, v103, v113
	s_and_b64 vcc, exec, s[44:45]
	ds_write_b32 v0, v9
	s_cbranch_vccnz .LBB0_407
	s_ashr_i32 s23, s22, 31
.LBB0_407:
	v_add_u32_e32 v0, v103, v114
	s_and_b64 vcc, exec, s[44:45]
	ds_write_b32 v0, v10
	s_cbranch_vccnz .LBB0_409
	s_ashr_i32 s23, s22, 31
.LBB0_409:
	v_add_u32_e32 v0, v103, v115
	s_and_b64 vcc, exec, s[44:45]
	ds_write_b32 v0, v11
	s_cbranch_vccnz .LBB0_411
	s_ashr_i32 s23, s22, 31
.LBB0_411:
	v_add_u32_e32 v0, v103, v116
	s_and_b64 vcc, exec, s[44:45]
	ds_write_b32 v0, v12
	s_cbranch_vccnz .LBB0_413
	s_ashr_i32 s23, s22, 31
.LBB0_413:
	v_add_u32_e32 v0, v103, v117
	s_and_b64 vcc, exec, s[44:45]
	ds_write_b32 v0, v13
	s_cbranch_vccnz .LBB0_415
	s_ashr_i32 s23, s22, 31
.LBB0_415:
	v_add_u32_e32 v0, v103, v118
	s_and_b64 vcc, exec, s[44:45]
	ds_write_b32 v0, v14
	s_cbranch_vccnz .LBB0_417
	s_ashr_i32 s23, s22, 31
.LBB0_417:
	v_add_u32_e32 v0, v103, v119
	s_and_b64 vcc, exec, s[44:45]
	ds_write_b32 v0, v15
	s_cbranch_vccnz .LBB0_419
	s_ashr_i32 s23, s22, 31
.LBB0_419:
	v_add_u32_e32 v0, v103, v120
	s_and_b64 vcc, exec, s[44:45]
	ds_write_b32 v0, v16
	s_cbranch_vccnz .LBB0_421
	s_ashr_i32 s23, s22, 31
.LBB0_421:
	v_add_u32_e32 v0, v103, v121
	s_and_b64 vcc, exec, s[44:45]
	ds_write_b32 v0, v17
	s_cbranch_vccnz .LBB0_423
	s_ashr_i32 s23, s22, 31
.LBB0_423:
	v_add_u32_e32 v0, v103, v122
	s_and_b64 vcc, exec, s[44:45]
	ds_write_b32 v0, v18
	s_cbranch_vccnz .LBB0_425
	s_ashr_i32 s23, s22, 31
.LBB0_425:
	v_add_u32_e32 v0, v103, v123
	s_and_b64 vcc, exec, s[44:45]
	ds_write_b32 v0, v19
	s_cbranch_vccnz .LBB0_427
	s_ashr_i32 s23, s22, 31
.LBB0_427:
	s_and_b64 vcc, exec, s[44:45]
	ds_write_b32 v0, v20 offset:264
	s_cbranch_vccnz .LBB0_429
	s_ashr_i32 s23, s22, 31
.LBB0_429:
	s_and_b64 vcc, exec, s[44:45]
	ds_write_b32 v0, v21 offset:528
	s_cbranch_vccnz .LBB0_431
	s_ashr_i32 s23, s22, 31
.LBB0_431:
	s_and_b64 vcc, exec, s[44:45]
	ds_write_b32 v0, v22 offset:792
	s_cbranch_vccnz .LBB0_433
	s_ashr_i32 s23, s22, 31
.LBB0_433:
	s_and_b64 vcc, exec, s[44:45]
	ds_write_b32 v0, v23 offset:1056
	s_cbranch_vccnz .LBB0_435
	s_ashr_i32 s23, s22, 31
.LBB0_435:
	s_and_b64 vcc, exec, s[44:45]
	ds_write_b32 v0, v24 offset:1320
	s_cbranch_vccnz .LBB0_437
	s_ashr_i32 s23, s22, 31
.LBB0_437:
	s_and_b64 vcc, exec, s[44:45]
	ds_write_b32 v0, v25 offset:1584
	s_cbranch_vccnz .LBB0_439
	s_ashr_i32 s23, s22, 31
.LBB0_439:
	s_and_b64 vcc, exec, s[44:45]
	ds_write_b32 v0, v26 offset:1848
	s_cbranch_vccnz .LBB0_441
	s_ashr_i32 s23, s22, 31
.LBB0_441:
	s_and_b64 vcc, exec, s[44:45]
	ds_write_b32 v0, v27 offset:2112
	s_cbranch_vccnz .LBB0_443
	s_ashr_i32 s23, s22, 31
.LBB0_443:
	s_and_b64 vcc, exec, s[44:45]
	ds_write_b32 v0, v28 offset:2376
	s_cbranch_vccnz .LBB0_445
	s_ashr_i32 s23, s22, 31
.LBB0_445:
	s_and_b64 vcc, exec, s[44:45]
	ds_write_b32 v0, v29 offset:2640
	s_cbranch_vccnz .LBB0_447
	s_ashr_i32 s23, s22, 31
.LBB0_447:
	s_and_b64 vcc, exec, s[58:59]
	ds_write_b32 v0, v30 offset:2904
	s_cbranch_vccz .LBB0_449
	s_ashr_i32 s23, s22, 31
	v_mov_b32_e32 v1, v31
	s_cbranch_execnz .LBB0_382
	s_branch .LBB0_381
